# v_full3 + row-scale phases: the four intra-row hops of each wave sum use DPP adds instead of ds_bpermute (bit-identical sums)
# speedup vs baseline: 1.0207x; 1.0207x over previous
.LBB0_744:
	v_ashrrev_i32_e32 v1, 31, v0
	v_lshlrev_b64 v[4:5], 11, v[0:1]
	v_lshl_add_u64 v[4:5], v[2:3], 0, v[4:5]
	global_load_dwordx2 v[36:37], v[4:5], off
	global_load_dwordx2 v[38:39], v[4:5], off offset:512
	global_load_dwordx2 v[40:41], v[4:5], off offset:1024
	global_load_dwordx2 v[42:43], v[4:5], off offset:1536
	v_or_b32_e32 v8, 1, v0
	v_ashrrev_i32_e32 v9, 31, v8
	v_lshlrev_b64 v[4:5], 11, v[8:9]
	s_waitcnt lgkmcnt(0)
	v_or_b32_e32 v6, 2, v0
	v_lshl_add_u64 v[4:5], v[2:3], 0, v[4:5]
	v_ashrrev_i32_e32 v7, 31, v6
	global_load_dwordx2 v[32:33], v[4:5], off
	global_load_dwordx2 v[30:31], v[4:5], off offset:512
	global_load_dwordx2 v[28:29], v[4:5], off offset:1024
	global_load_dwordx2 v[24:25], v[4:5], off offset:1536
	v_lshlrev_b64 v[4:5], 11, v[6:7]
	v_lshl_add_u64 v[4:5], v[2:3], 0, v[4:5]
	global_load_dwordx2 v[20:21], v[4:5], off
	global_load_dwordx2 v[16:17], v[4:5], off offset:512
	global_load_dwordx2 v[12:13], v[4:5], off offset:1024
	global_load_dwordx2 v[10:11], v[4:5], off offset:1536
	v_or_b32_e32 v4, 3, v0
	v_ashrrev_i32_e32 v5, 31, v4
	v_lshlrev_b64 v[14:15], 11, v[4:5]
	v_lshl_add_u64 v[14:15], v[2:3], 0, v[14:15]
	global_load_dwordx2 v[26:27], v[14:15], off
	global_load_dwordx2 v[22:23], v[14:15], off offset:512
	global_load_dwordx2 v[18:19], v[14:15], off offset:1024
	s_nop 0
	global_load_dwordx2 v[14:15], v[14:15], off offset:1536
	s_waitcnt vmcnt(15)
	v_lshlrev_b32_e32 v44, 16, v36
	v_and_b32_e32 v36, 0xffff0000, v36
	v_lshlrev_b32_e32 v45, 16, v37
	v_and_b32_e32 v37, 0xffff0000, v37
	v_mul_f32_e32 v36, v36, v36
	v_mul_f32_e32 v37, v37, v37
	v_fmac_f32_e32 v36, v44, v44
	v_fmac_f32_e32 v37, v45, v45
	v_add_f32_e32 v36, v36, v37
	s_waitcnt vmcnt(14)
	v_lshlrev_b32_e32 v37, 16, v38
	v_and_b32_e32 v38, 0xffff0000, v38
	v_lshlrev_b32_e32 v44, 16, v39
	v_and_b32_e32 v39, 0xffff0000, v39
	v_mul_f32_e32 v38, v38, v38
	v_fmac_f32_e32 v38, v37, v37
	v_mul_f32_e32 v37, v39, v39
	v_fmac_f32_e32 v37, v44, v44
	v_add_f32_e32 v37, v38, v37
	s_waitcnt vmcnt(13)
	v_and_b32_e32 v38, 0xffff0000, v40
	v_add_f32_e32 v36, v36, v37
	v_lshlrev_b32_e32 v37, 16, v40
	v_and_b32_e32 v40, 0xffff0000, v41
	v_mul_f32_e32 v38, v38, v38
	v_lshlrev_b32_e32 v39, 16, v41
	v_fmac_f32_e32 v38, v37, v37
	v_mul_f32_e32 v37, v40, v40
	v_fmac_f32_e32 v37, v39, v39
	v_add_f32_e32 v37, v38, v37
	s_waitcnt vmcnt(12)
	v_and_b32_e32 v38, 0xffff0000, v42
	v_add_f32_e32 v36, v36, v37
	v_lshlrev_b32_e32 v37, 16, v42
	v_and_b32_e32 v40, 0xffff0000, v43
	v_mul_f32_e32 v38, v38, v38
	v_lshlrev_b32_e32 v39, 16, v43
	v_fmac_f32_e32 v38, v37, v37
	v_mul_f32_e32 v37, v40, v40
	v_fmac_f32_e32 v37, v39, v39
	v_add_f32_e32 v37, v38, v37
	v_add_f32_e32 v36, v36, v37
	s_nop 1
	v_add_f32_dpp v36, v36, v36 quad_perm:[1,0,3,2] row_mask:0xf bank_mask:0xf
	s_nop 1
	v_add_f32_dpp v36, v36, v36 quad_perm:[2,3,0,1] row_mask:0xf bank_mask:0xf
	s_nop 1
	v_add_f32_dpp v36, v36, v36 row_half_mirror row_mask:0xf bank_mask:0xf
	s_nop 1
	v_add_f32_dpp v36, v36, v36 row_mirror row_mask:0xf bank_mask:0xf
	s_nop 0
	ds_bpermute_b32 v37, v76, v36
	s_waitcnt lgkmcnt(0)
	v_add_f32_e32 v36, v36, v37
	ds_bpermute_b32 v37, v77, v36
	s_and_saveexec_b64 s[6:7], vcc
	s_cbranch_execz .LBB0_746
	s_waitcnt lgkmcnt(0)
	v_add_f32_e32 v36, v36, v37
	v_fmamk_f32 v36, v36, 0x3a800000, v181
	s_mov_b32 s0, 0x800000
	v_mul_f32_e32 v37, 0x4b800000, v36
	v_cmp_gt_f32_e64 s[0:1], s0, v36
	v_readlane_b32 s8, v253, 32
	v_readlane_b32 s9, v253, 33
	v_cndmask_b32_e64 v36, v36, v37, s[0:1]
	v_rsq_f32_e32 v38, v36
	v_lshl_add_u64 v[36:37], v[0:1], 2, s[8:9]
	v_mul_f32_e32 v1, 0x45800000, v38
	v_cndmask_b32_e64 v1, v38, v1, s[0:1]
	global_store_dword v[36:37], v1, off
.LBB0_746:
	s_or_b64 exec, exec, s[6:7]
	s_waitcnt vmcnt(11)
	v_lshlrev_b32_e32 v1, 16, v32
	v_and_b32_e32 v32, 0xffff0000, v32
	v_lshlrev_b32_e32 v36, 16, v33
	v_and_b32_e32 v33, 0xffff0000, v33
	v_mul_f32_e32 v32, v32, v32
	v_fmac_f32_e32 v32, v1, v1
	v_mul_f32_e32 v1, v33, v33
	v_fmac_f32_e32 v1, v36, v36
	v_add_f32_e32 v1, v32, v1
	s_waitcnt vmcnt(10)
	v_lshlrev_b32_e32 v32, 16, v30
	v_and_b32_e32 v30, 0xffff0000, v30
	v_lshlrev_b32_e32 v33, 16, v31
	v_and_b32_e32 v31, 0xffff0000, v31
	v_mul_f32_e32 v30, v30, v30
	v_mul_f32_e32 v31, v31, v31
	v_fmac_f32_e32 v30, v32, v32
	v_fmac_f32_e32 v31, v33, v33
	v_add_f32_e32 v30, v30, v31
	v_add_f32_e32 v1, v1, v30
	s_waitcnt vmcnt(9)
	v_lshlrev_b32_e32 v30, 16, v28
	v_and_b32_e32 v28, 0xffff0000, v28
	v_lshlrev_b32_e32 v31, 16, v29
	v_and_b32_e32 v29, 0xffff0000, v29
	v_mul_f32_e32 v28, v28, v28
	v_mul_f32_e32 v29, v29, v29
	v_fmac_f32_e32 v28, v30, v30
	v_fmac_f32_e32 v29, v31, v31
	v_add_f32_e32 v28, v28, v29
	v_add_f32_e32 v1, v1, v28
	s_waitcnt vmcnt(8)
	v_lshlrev_b32_e32 v28, 16, v24
	v_and_b32_e32 v24, 0xffff0000, v24
	v_lshlrev_b32_e32 v29, 16, v25
	v_and_b32_e32 v25, 0xffff0000, v25
	v_mul_f32_e32 v24, v24, v24
	v_mul_f32_e32 v25, v25, v25
	v_fmac_f32_e32 v24, v28, v28
	v_fmac_f32_e32 v25, v29, v29
	v_add_f32_e32 v24, v24, v25
	v_add_f32_e32 v1, v1, v24
	s_nop 1
	v_add_f32_dpp v1, v1, v1 quad_perm:[1,0,3,2] row_mask:0xf bank_mask:0xf
	s_nop 1
	v_add_f32_dpp v1, v1, v1 quad_perm:[2,3,0,1] row_mask:0xf bank_mask:0xf
	s_nop 1
	v_add_f32_dpp v1, v1, v1 row_half_mirror row_mask:0xf bank_mask:0xf
	s_nop 1
	v_add_f32_dpp v1, v1, v1 row_mirror row_mask:0xf bank_mask:0xf
	s_nop 0
	ds_bpermute_b32 v24, v76, v1
	s_waitcnt lgkmcnt(0)
	v_add_f32_e32 v1, v1, v24
	ds_bpermute_b32 v24, v77, v1
	s_and_saveexec_b64 s[6:7], vcc
	s_cbranch_execz .LBB0_748
	s_waitcnt lgkmcnt(0)
	v_add_f32_e32 v1, v1, v24
	v_fmamk_f32 v1, v1, 0x3a800000, v181
	s_mov_b32 s0, 0x800000
	v_mul_f32_e32 v24, 0x4b800000, v1
	v_cmp_gt_f32_e64 s[0:1], s0, v1
	v_readlane_b32 s8, v253, 32
	v_readlane_b32 s9, v253, 33
	v_cndmask_b32_e64 v1, v1, v24, s[0:1]
	v_rsq_f32_e32 v1, v1
	v_lshl_add_u64 v[8:9], v[8:9], 2, s[8:9]
	v_mul_f32_e32 v24, 0x45800000, v1
	v_cndmask_b32_e64 v1, v1, v24, s[0:1]
	global_store_dword v[8:9], v1, off
.LBB0_748:
	s_or_b64 exec, exec, s[6:7]
	s_waitcnt vmcnt(7)
	v_and_b32_e32 v8, 0xffff0000, v20
	v_lshlrev_b32_e32 v1, 16, v20
	v_and_b32_e32 v20, 0xffff0000, v21
	v_mul_f32_e32 v8, v8, v8
	v_lshlrev_b32_e32 v9, 16, v21
	v_fmac_f32_e32 v8, v1, v1
	v_mul_f32_e32 v1, v20, v20
	v_fmac_f32_e32 v1, v9, v9
	s_waitcnt vmcnt(6)
	v_and_b32_e32 v9, 0xffff0000, v16
	v_add_f32_e32 v1, v8, v1
	v_lshlrev_b32_e32 v8, 16, v16
	v_lshlrev_b32_e32 v16, 16, v17
	v_and_b32_e32 v17, 0xffff0000, v17
	v_mul_f32_e32 v9, v9, v9
	v_fmac_f32_e32 v9, v8, v8
	v_mul_f32_e32 v8, v17, v17
	v_fmac_f32_e32 v8, v16, v16
	v_add_f32_e32 v8, v9, v8
	s_waitcnt vmcnt(5)
	v_and_b32_e32 v9, 0xffff0000, v12
	v_add_f32_e32 v1, v1, v8
	v_lshlrev_b32_e32 v8, 16, v12
	v_lshlrev_b32_e32 v12, 16, v13
	v_and_b32_e32 v13, 0xffff0000, v13
	v_mul_f32_e32 v9, v9, v9
	v_fmac_f32_e32 v9, v8, v8
	v_mul_f32_e32 v8, v13, v13
	v_fmac_f32_e32 v8, v12, v12
	v_add_f32_e32 v8, v9, v8
	s_waitcnt vmcnt(4)
	v_and_b32_e32 v9, 0xffff0000, v10
	v_add_f32_e32 v1, v1, v8
	v_lshlrev_b32_e32 v8, 16, v10
	v_lshlrev_b32_e32 v10, 16, v11
	v_and_b32_e32 v11, 0xffff0000, v11
	v_mul_f32_e32 v9, v9, v9
	v_fmac_f32_e32 v9, v8, v8
	v_mul_f32_e32 v8, v11, v11
	v_fmac_f32_e32 v8, v10, v10
	v_add_f32_e32 v8, v9, v8
	v_add_f32_e32 v1, v1, v8
	s_nop 1
	v_add_f32_dpp v1, v1, v1 quad_perm:[1,0,3,2] row_mask:0xf bank_mask:0xf
	s_nop 1
	v_add_f32_dpp v1, v1, v1 quad_perm:[2,3,0,1] row_mask:0xf bank_mask:0xf
	s_nop 1
	v_add_f32_dpp v1, v1, v1 row_half_mirror row_mask:0xf bank_mask:0xf
	s_nop 1
	v_add_f32_dpp v1, v1, v1 row_mirror row_mask:0xf bank_mask:0xf
	s_nop 0
	ds_bpermute_b32 v8, v76, v1
	s_waitcnt lgkmcnt(0)
	v_add_f32_e32 v1, v1, v8
	ds_bpermute_b32 v8, v77, v1
	s_and_saveexec_b64 s[6:7], vcc
	s_cbranch_execz .LBB0_750
	s_waitcnt lgkmcnt(0)
	v_add_f32_e32 v1, v1, v8
	v_fmamk_f32 v1, v1, 0x3a800000, v181
	s_mov_b32 s0, 0x800000
	v_mul_f32_e32 v8, 0x4b800000, v1
	v_cmp_gt_f32_e64 s[0:1], s0, v1
	v_readlane_b32 s8, v253, 32
	v_readlane_b32 s9, v253, 33
	v_cndmask_b32_e64 v1, v1, v8, s[0:1]
	v_rsq_f32_e32 v1, v1
	v_lshl_add_u64 v[6:7], v[6:7], 2, s[8:9]
	v_mul_f32_e32 v8, 0x45800000, v1
	v_cndmask_b32_e64 v1, v1, v8, s[0:1]
	global_store_dword v[6:7], v1, off
.LBB0_750:
	s_or_b64 exec, exec, s[6:7]
	s_waitcnt vmcnt(3)
	v_and_b32_e32 v6, 0xffff0000, v26
	v_lshlrev_b32_e32 v1, 16, v26
	s_waitcnt lgkmcnt(0)
	v_and_b32_e32 v8, 0xffff0000, v27
	v_mul_f32_e32 v6, v6, v6
	v_lshlrev_b32_e32 v7, 16, v27
	v_fmac_f32_e32 v6, v1, v1
	v_mul_f32_e32 v1, v8, v8
	v_fmac_f32_e32 v1, v7, v7
	s_waitcnt vmcnt(2)
	v_and_b32_e32 v7, 0xffff0000, v22
	v_add_f32_e32 v1, v6, v1
	v_lshlrev_b32_e32 v6, 16, v22
	v_and_b32_e32 v9, 0xffff0000, v23
	v_mul_f32_e32 v7, v7, v7
	v_lshlrev_b32_e32 v8, 16, v23
	v_fmac_f32_e32 v7, v6, v6
	v_mul_f32_e32 v6, v9, v9
	v_fmac_f32_e32 v6, v8, v8
	v_add_f32_e32 v6, v7, v6
	s_waitcnt vmcnt(1)
	v_and_b32_e32 v7, 0xffff0000, v18
	v_add_f32_e32 v1, v1, v6
	v_lshlrev_b32_e32 v6, 16, v18
	v_and_b32_e32 v9, 0xffff0000, v19
	v_mul_f32_e32 v7, v7, v7
	v_lshlrev_b32_e32 v8, 16, v19
	v_fmac_f32_e32 v7, v6, v6
	v_mul_f32_e32 v6, v9, v9
	v_fmac_f32_e32 v6, v8, v8
	v_add_f32_e32 v6, v7, v6
	s_waitcnt vmcnt(0)
	v_and_b32_e32 v7, 0xffff0000, v14
	v_add_f32_e32 v1, v1, v6
	v_lshlrev_b32_e32 v6, 16, v14
	v_and_b32_e32 v9, 0xffff0000, v15
	v_mul_f32_e32 v7, v7, v7
	v_lshlrev_b32_e32 v8, 16, v15
	v_fmac_f32_e32 v7, v6, v6
	v_mul_f32_e32 v6, v9, v9
	v_fmac_f32_e32 v6, v8, v8
	v_add_f32_e32 v6, v7, v6
	v_add_f32_e32 v1, v1, v6
	s_nop 1
	v_add_f32_dpp v1, v1, v1 quad_perm:[1,0,3,2] row_mask:0xf bank_mask:0xf
	s_nop 1
	v_add_f32_dpp v1, v1, v1 quad_perm:[2,3,0,1] row_mask:0xf bank_mask:0xf
	s_nop 1
	v_add_f32_dpp v1, v1, v1 row_half_mirror row_mask:0xf bank_mask:0xf
	s_nop 1
	v_add_f32_dpp v1, v1, v1 row_mirror row_mask:0xf bank_mask:0xf
	s_nop 0
	ds_bpermute_b32 v6, v76, v1
	s_waitcnt lgkmcnt(0)
	v_add_f32_e32 v1, v1, v6
	ds_bpermute_b32 v6, v77, v1
	s_and_saveexec_b64 s[6:7], vcc
	s_cbranch_execz .LBB0_743
	v_readlane_b32 s0, v253, 32
	v_readlane_b32 s1, v253, 33
	s_waitcnt lgkmcnt(0)
	v_add_f32_e32 v1, v1, v6
	v_fmamk_f32 v1, v1, 0x3a800000, v181
	v_lshl_add_u64 v[4:5], v[4:5], 2, s[0:1]
	s_mov_b32 s0, 0x800000
	v_cmp_gt_f32_e64 s[0:1], s0, v1
	v_mul_f32_e32 v6, 0x4b800000, v1
	s_nop 0
	v_cndmask_b32_e64 v1, v1, v6, s[0:1]
	v_rsq_f32_e32 v1, v1
	s_nop 0
	v_mul_f32_e32 v6, 0x45800000, v1
	v_cndmask_b32_e64 v1, v1, v6, s[0:1]
	global_store_dword v[4:5], v1, off
	s_branch .LBB0_743

.LBB0_757:
	s_or_b64 exec, exec, s[6:7]
	v_mul_f32_e32 v15, v15, v15
	v_mul_f32_e32 v13, v13, v13
	v_mul_f32_e32 v11, v11, v11
	v_mul_f32_e32 v9, v9, v9
	v_fmac_f32_e32 v15, v14, v14
	v_fmac_f32_e32 v13, v12, v12
	v_fmac_f32_e32 v11, v10, v10
	v_fmac_f32_e32 v9, v8, v8
	v_mul_f32_e32 v7, v7, v7
	v_mul_f32_e32 v5, v5, v5
	v_add_f32_e32 v12, v15, v13
	v_add_f32_e32 v8, v11, v9
	v_fmac_f32_e32 v7, v6, v6
	v_fmac_f32_e32 v5, v4, v4
	v_mul_f32_e32 v3, v3, v3
	v_mul_f32_e32 v1, v1, v1
	v_add_f32_e32 v8, v12, v8
	v_add_f32_e32 v4, v7, v5
	v_fmac_f32_e32 v3, v2, v2
	v_fmac_f32_e32 v1, v0, v0
	v_add_f32_e32 v4, v4, v8
	v_add_f32_e32 v0, v3, v1
	v_add_f32_e32 v0, v0, v4
	s_nop 1
	v_add_f32_dpp v0, v0, v0 quad_perm:[1,0,3,2] row_mask:0xf bank_mask:0xf
	s_nop 1
	v_add_f32_dpp v0, v0, v0 quad_perm:[2,3,0,1] row_mask:0xf bank_mask:0xf
	s_nop 1
	v_add_f32_dpp v0, v0, v0 row_half_mirror row_mask:0xf bank_mask:0xf
	s_nop 1
	v_add_f32_dpp v0, v0, v0 row_mirror row_mask:0xf bank_mask:0xf
	s_nop 0
	ds_bpermute_b32 v1, v76, v0
	s_waitcnt lgkmcnt(0)
	v_add_f32_e32 v0, v0, v1
	ds_bpermute_b32 v1, v77, v0
	s_and_saveexec_b64 s[6:7], s[2:3]
	s_cbranch_execz .LBB0_754
	s_waitcnt lgkmcnt(0)
	v_add_f32_e32 v0, v0, v1
	v_fmamk_f32 v0, v0, 0x3a800000, v181
	s_mov_b32 s8, 0x800000
	v_mul_f32_e32 v1, 0x4b800000, v0
	v_cmp_gt_f32_e32 vcc, s8, v0
	v_readlane_b32 s8, v253, 32
	v_readlane_b32 s9, v253, 33
	v_cndmask_b32_e32 v0, v0, v1, vcc
	v_rsq_f32_e32 v2, v0
	v_lshl_add_u64 v[0:1], v[48:49], 2, s[8:9]
	v_mul_f32_e32 v3, 0x45800000, v2
	v_cndmask_b32_e32 v2, v2, v3, vcc
	global_store_dword v[0:1], v2, off
	s_branch .LBB0_754

.LBB0_1672:
	v_ashrrev_i32_e32 v1, 31, v0
	v_lshlrev_b64 v[4:5], 11, v[0:1]
	v_lshl_add_u64 v[4:5], v[2:3], 0, v[4:5]
	global_load_dwordx2 v[42:43], v[4:5], off
	global_load_dwordx2 v[44:45], v[4:5], off offset:512
	global_load_dwordx2 v[46:47], v[4:5], off offset:1024
	global_load_dwordx2 v[48:49], v[4:5], off offset:1536
	v_or_b32_e32 v8, 1, v0
	v_ashrrev_i32_e32 v9, 31, v8
	v_lshlrev_b64 v[4:5], 11, v[8:9]
	s_waitcnt lgkmcnt(0)
	v_or_b32_e32 v6, 2, v0
	v_lshl_add_u64 v[4:5], v[2:3], 0, v[4:5]
	v_ashrrev_i32_e32 v7, 31, v6
	global_load_dwordx2 v[32:33], v[4:5], off
	global_load_dwordx2 v[30:31], v[4:5], off offset:512
	global_load_dwordx2 v[28:29], v[4:5], off offset:1024
	global_load_dwordx2 v[24:25], v[4:5], off offset:1536
	v_lshlrev_b64 v[4:5], 11, v[6:7]
	v_lshl_add_u64 v[4:5], v[2:3], 0, v[4:5]
	global_load_dwordx2 v[20:21], v[4:5], off
	global_load_dwordx2 v[16:17], v[4:5], off offset:512
	global_load_dwordx2 v[12:13], v[4:5], off offset:1024
	global_load_dwordx2 v[10:11], v[4:5], off offset:1536
	v_or_b32_e32 v4, 3, v0
	v_ashrrev_i32_e32 v5, 31, v4
	v_lshlrev_b64 v[14:15], 11, v[4:5]
	v_lshl_add_u64 v[14:15], v[2:3], 0, v[14:15]
	global_load_dwordx2 v[26:27], v[14:15], off
	global_load_dwordx2 v[22:23], v[14:15], off offset:512
	global_load_dwordx2 v[18:19], v[14:15], off offset:1024
	s_nop 0
	global_load_dwordx2 v[14:15], v[14:15], off offset:1536
	s_waitcnt vmcnt(15)
	v_lshlrev_b32_e32 v50, 16, v42
	v_and_b32_e32 v42, 0xffff0000, v42
	v_lshlrev_b32_e32 v51, 16, v43
	v_and_b32_e32 v43, 0xffff0000, v43
	v_mul_f32_e32 v42, v42, v42
	v_mul_f32_e32 v43, v43, v43
	v_fmac_f32_e32 v42, v50, v50
	v_fmac_f32_e32 v43, v51, v51
	v_add_f32_e32 v42, v42, v43
	s_waitcnt vmcnt(14)
	v_lshlrev_b32_e32 v43, 16, v44
	v_and_b32_e32 v44, 0xffff0000, v44
	v_lshlrev_b32_e32 v50, 16, v45
	v_and_b32_e32 v45, 0xffff0000, v45
	v_mul_f32_e32 v44, v44, v44
	v_fmac_f32_e32 v44, v43, v43
	v_mul_f32_e32 v43, v45, v45
	v_fmac_f32_e32 v43, v50, v50
	v_add_f32_e32 v43, v44, v43
	s_waitcnt vmcnt(13)
	v_and_b32_e32 v44, 0xffff0000, v46
	v_add_f32_e32 v42, v42, v43
	v_lshlrev_b32_e32 v43, 16, v46
	v_and_b32_e32 v46, 0xffff0000, v47
	v_mul_f32_e32 v44, v44, v44
	v_lshlrev_b32_e32 v45, 16, v47
	v_fmac_f32_e32 v44, v43, v43
	v_mul_f32_e32 v43, v46, v46
	v_fmac_f32_e32 v43, v45, v45
	v_add_f32_e32 v43, v44, v43
	s_waitcnt vmcnt(12)
	v_and_b32_e32 v44, 0xffff0000, v48
	v_add_f32_e32 v42, v42, v43
	v_lshlrev_b32_e32 v43, 16, v48
	v_and_b32_e32 v46, 0xffff0000, v49
	v_mul_f32_e32 v44, v44, v44
	v_lshlrev_b32_e32 v45, 16, v49
	v_fmac_f32_e32 v44, v43, v43
	v_mul_f32_e32 v43, v46, v46
	v_fmac_f32_e32 v43, v45, v45
	v_add_f32_e32 v43, v44, v43
	v_add_f32_e32 v42, v42, v43
	s_nop 1
	v_add_f32_dpp v42, v42, v42 quad_perm:[1,0,3,2] row_mask:0xf bank_mask:0xf
	s_nop 1
	v_add_f32_dpp v42, v42, v42 quad_perm:[2,3,0,1] row_mask:0xf bank_mask:0xf
	s_nop 1
	v_add_f32_dpp v42, v42, v42 row_half_mirror row_mask:0xf bank_mask:0xf
	s_nop 1
	v_add_f32_dpp v42, v42, v42 row_mirror row_mask:0xf bank_mask:0xf
	s_nop 0
	ds_bpermute_b32 v43, v38, v42
	s_waitcnt lgkmcnt(0)
	v_add_f32_e32 v42, v42, v43
	ds_bpermute_b32 v43, v39, v42
	s_and_saveexec_b64 s[6:7], vcc
	s_cbranch_execz .LBB0_1674
	s_waitcnt lgkmcnt(0)
	v_add_f32_e32 v42, v42, v43
	v_fmamk_f32 v42, v42, 0x3a800000, v181
	s_mov_b32 s0, 0x800000
	v_mul_f32_e32 v43, 0x4b800000, v42
	v_cmp_gt_f32_e64 s[0:1], s0, v42
	v_readlane_b32 s8, v253, 32
	v_readlane_b32 s9, v253, 33
	v_cndmask_b32_e64 v42, v42, v43, s[0:1]
	v_rsq_f32_e32 v44, v42
	v_lshl_add_u64 v[42:43], v[0:1], 2, s[8:9]
	v_mul_f32_e32 v1, 0x45800000, v44
	v_cndmask_b32_e64 v1, v44, v1, s[0:1]
	global_store_dword v[42:43], v1, off
.LBB0_1674:
	s_or_b64 exec, exec, s[6:7]
	s_waitcnt vmcnt(11)
	v_lshlrev_b32_e32 v1, 16, v32
	v_and_b32_e32 v32, 0xffff0000, v32
	v_lshlrev_b32_e32 v42, 16, v33
	v_and_b32_e32 v33, 0xffff0000, v33
	v_mul_f32_e32 v32, v32, v32
	v_fmac_f32_e32 v32, v1, v1
	v_mul_f32_e32 v1, v33, v33
	v_fmac_f32_e32 v1, v42, v42
	v_add_f32_e32 v1, v32, v1
	s_waitcnt vmcnt(10)
	v_lshlrev_b32_e32 v32, 16, v30
	v_and_b32_e32 v30, 0xffff0000, v30
	v_lshlrev_b32_e32 v33, 16, v31
	v_and_b32_e32 v31, 0xffff0000, v31
	v_mul_f32_e32 v30, v30, v30
	v_mul_f32_e32 v31, v31, v31
	v_fmac_f32_e32 v30, v32, v32
	v_fmac_f32_e32 v31, v33, v33
	v_add_f32_e32 v30, v30, v31
	v_add_f32_e32 v1, v1, v30
	s_waitcnt vmcnt(9)
	v_lshlrev_b32_e32 v30, 16, v28
	v_and_b32_e32 v28, 0xffff0000, v28
	v_lshlrev_b32_e32 v31, 16, v29
	v_and_b32_e32 v29, 0xffff0000, v29
	v_mul_f32_e32 v28, v28, v28
	v_mul_f32_e32 v29, v29, v29
	v_fmac_f32_e32 v28, v30, v30
	v_fmac_f32_e32 v29, v31, v31
	v_add_f32_e32 v28, v28, v29
	v_add_f32_e32 v1, v1, v28
	s_waitcnt vmcnt(8)
	v_lshlrev_b32_e32 v28, 16, v24
	v_and_b32_e32 v24, 0xffff0000, v24
	v_lshlrev_b32_e32 v29, 16, v25
	v_and_b32_e32 v25, 0xffff0000, v25
	v_mul_f32_e32 v24, v24, v24
	v_mul_f32_e32 v25, v25, v25
	v_fmac_f32_e32 v24, v28, v28
	v_fmac_f32_e32 v25, v29, v29
	v_add_f32_e32 v24, v24, v25
	v_add_f32_e32 v1, v1, v24
	s_nop 1
	v_add_f32_dpp v1, v1, v1 quad_perm:[1,0,3,2] row_mask:0xf bank_mask:0xf
	s_nop 1
	v_add_f32_dpp v1, v1, v1 quad_perm:[2,3,0,1] row_mask:0xf bank_mask:0xf
	s_nop 1
	v_add_f32_dpp v1, v1, v1 row_half_mirror row_mask:0xf bank_mask:0xf
	s_nop 1
	v_add_f32_dpp v1, v1, v1 row_mirror row_mask:0xf bank_mask:0xf
	s_nop 0
	ds_bpermute_b32 v24, v38, v1
	s_waitcnt lgkmcnt(0)
	v_add_f32_e32 v1, v1, v24
	ds_bpermute_b32 v24, v39, v1
	s_and_saveexec_b64 s[6:7], vcc
	s_cbranch_execz .LBB0_1676
	s_waitcnt lgkmcnt(0)
	v_add_f32_e32 v1, v1, v24
	v_fmamk_f32 v1, v1, 0x3a800000, v181
	s_mov_b32 s0, 0x800000
	v_mul_f32_e32 v24, 0x4b800000, v1
	v_cmp_gt_f32_e64 s[0:1], s0, v1
	v_readlane_b32 s8, v253, 32
	v_readlane_b32 s9, v253, 33
	v_cndmask_b32_e64 v1, v1, v24, s[0:1]
	v_rsq_f32_e32 v1, v1
	v_lshl_add_u64 v[8:9], v[8:9], 2, s[8:9]
	v_mul_f32_e32 v24, 0x45800000, v1
	v_cndmask_b32_e64 v1, v1, v24, s[0:1]
	global_store_dword v[8:9], v1, off
.LBB0_1676:
	s_or_b64 exec, exec, s[6:7]
	s_waitcnt vmcnt(7)
	v_and_b32_e32 v8, 0xffff0000, v20
	v_lshlrev_b32_e32 v1, 16, v20
	v_and_b32_e32 v20, 0xffff0000, v21
	v_mul_f32_e32 v8, v8, v8
	v_lshlrev_b32_e32 v9, 16, v21
	v_fmac_f32_e32 v8, v1, v1
	v_mul_f32_e32 v1, v20, v20
	v_fmac_f32_e32 v1, v9, v9
	s_waitcnt vmcnt(6)
	v_and_b32_e32 v9, 0xffff0000, v16
	v_add_f32_e32 v1, v8, v1
	v_lshlrev_b32_e32 v8, 16, v16
	v_lshlrev_b32_e32 v16, 16, v17
	v_and_b32_e32 v17, 0xffff0000, v17
	v_mul_f32_e32 v9, v9, v9
	v_fmac_f32_e32 v9, v8, v8
	v_mul_f32_e32 v8, v17, v17
	v_fmac_f32_e32 v8, v16, v16
	v_add_f32_e32 v8, v9, v8
	s_waitcnt vmcnt(5)
	v_and_b32_e32 v9, 0xffff0000, v12
	v_add_f32_e32 v1, v1, v8
	v_lshlrev_b32_e32 v8, 16, v12
	v_lshlrev_b32_e32 v12, 16, v13
	v_and_b32_e32 v13, 0xffff0000, v13
	v_mul_f32_e32 v9, v9, v9
	v_fmac_f32_e32 v9, v8, v8
	v_mul_f32_e32 v8, v13, v13
	v_fmac_f32_e32 v8, v12, v12
	v_add_f32_e32 v8, v9, v8
	s_waitcnt vmcnt(4)
	v_and_b32_e32 v9, 0xffff0000, v10
	v_add_f32_e32 v1, v1, v8
	v_lshlrev_b32_e32 v8, 16, v10
	v_lshlrev_b32_e32 v10, 16, v11
	v_and_b32_e32 v11, 0xffff0000, v11
	v_mul_f32_e32 v9, v9, v9
	v_fmac_f32_e32 v9, v8, v8
	v_mul_f32_e32 v8, v11, v11
	v_fmac_f32_e32 v8, v10, v10
	v_add_f32_e32 v8, v9, v8
	v_add_f32_e32 v1, v1, v8
	s_nop 1
	v_add_f32_dpp v1, v1, v1 quad_perm:[1,0,3,2] row_mask:0xf bank_mask:0xf
	s_nop 1
	v_add_f32_dpp v1, v1, v1 quad_perm:[2,3,0,1] row_mask:0xf bank_mask:0xf
	s_nop 1
	v_add_f32_dpp v1, v1, v1 row_half_mirror row_mask:0xf bank_mask:0xf
	s_nop 1
	v_add_f32_dpp v1, v1, v1 row_mirror row_mask:0xf bank_mask:0xf
	s_nop 0
	ds_bpermute_b32 v8, v38, v1
	s_waitcnt lgkmcnt(0)
	v_add_f32_e32 v1, v1, v8
	ds_bpermute_b32 v8, v39, v1
	s_and_saveexec_b64 s[6:7], vcc
	s_cbranch_execz .LBB0_1678
	s_waitcnt lgkmcnt(0)
	v_add_f32_e32 v1, v1, v8
	v_fmamk_f32 v1, v1, 0x3a800000, v181
	s_mov_b32 s0, 0x800000
	v_mul_f32_e32 v8, 0x4b800000, v1
	v_cmp_gt_f32_e64 s[0:1], s0, v1
	v_readlane_b32 s8, v253, 32
	v_readlane_b32 s9, v253, 33
	v_cndmask_b32_e64 v1, v1, v8, s[0:1]
	v_rsq_f32_e32 v1, v1
	v_lshl_add_u64 v[6:7], v[6:7], 2, s[8:9]
	v_mul_f32_e32 v8, 0x45800000, v1
	v_cndmask_b32_e64 v1, v1, v8, s[0:1]
	global_store_dword v[6:7], v1, off
.LBB0_1678:
	s_or_b64 exec, exec, s[6:7]
	s_waitcnt vmcnt(3)
	v_and_b32_e32 v6, 0xffff0000, v26
	v_lshlrev_b32_e32 v1, 16, v26
	s_waitcnt lgkmcnt(0)
	v_and_b32_e32 v8, 0xffff0000, v27
	v_mul_f32_e32 v6, v6, v6
	v_lshlrev_b32_e32 v7, 16, v27
	v_fmac_f32_e32 v6, v1, v1
	v_mul_f32_e32 v1, v8, v8
	v_fmac_f32_e32 v1, v7, v7
	s_waitcnt vmcnt(2)
	v_and_b32_e32 v7, 0xffff0000, v22
	v_add_f32_e32 v1, v6, v1
	v_lshlrev_b32_e32 v6, 16, v22
	v_and_b32_e32 v9, 0xffff0000, v23
	v_mul_f32_e32 v7, v7, v7
	v_lshlrev_b32_e32 v8, 16, v23
	v_fmac_f32_e32 v7, v6, v6
	v_mul_f32_e32 v6, v9, v9
	v_fmac_f32_e32 v6, v8, v8
	v_add_f32_e32 v6, v7, v6
	s_waitcnt vmcnt(1)
	v_and_b32_e32 v7, 0xffff0000, v18
	v_add_f32_e32 v1, v1, v6
	v_lshlrev_b32_e32 v6, 16, v18
	v_and_b32_e32 v9, 0xffff0000, v19
	v_mul_f32_e32 v7, v7, v7
	v_lshlrev_b32_e32 v8, 16, v19
	v_fmac_f32_e32 v7, v6, v6
	v_mul_f32_e32 v6, v9, v9
	v_fmac_f32_e32 v6, v8, v8
	v_add_f32_e32 v6, v7, v6
	s_waitcnt vmcnt(0)
	v_and_b32_e32 v7, 0xffff0000, v14
	v_add_f32_e32 v1, v1, v6
	v_lshlrev_b32_e32 v6, 16, v14
	v_and_b32_e32 v9, 0xffff0000, v15
	v_mul_f32_e32 v7, v7, v7
	v_lshlrev_b32_e32 v8, 16, v15
	v_fmac_f32_e32 v7, v6, v6
	v_mul_f32_e32 v6, v9, v9
	v_fmac_f32_e32 v6, v8, v8
	v_add_f32_e32 v6, v7, v6
	v_add_f32_e32 v1, v1, v6
	s_nop 1
	v_add_f32_dpp v1, v1, v1 quad_perm:[1,0,3,2] row_mask:0xf bank_mask:0xf
	s_nop 1
	v_add_f32_dpp v1, v1, v1 quad_perm:[2,3,0,1] row_mask:0xf bank_mask:0xf
	s_nop 1
	v_add_f32_dpp v1, v1, v1 row_half_mirror row_mask:0xf bank_mask:0xf
	s_nop 1
	v_add_f32_dpp v1, v1, v1 row_mirror row_mask:0xf bank_mask:0xf
	s_nop 0
	ds_bpermute_b32 v6, v38, v1
	s_waitcnt lgkmcnt(0)
	v_add_f32_e32 v1, v1, v6
	ds_bpermute_b32 v6, v39, v1
	s_and_saveexec_b64 s[6:7], vcc
	s_cbranch_execz .LBB0_1671
	v_readlane_b32 s0, v253, 32
	v_readlane_b32 s1, v253, 33
	s_waitcnt lgkmcnt(0)
	v_add_f32_e32 v1, v1, v6
	v_fmamk_f32 v1, v1, 0x3a800000, v181
	v_lshl_add_u64 v[4:5], v[4:5], 2, s[0:1]
	s_mov_b32 s0, 0x800000
	v_cmp_gt_f32_e64 s[0:1], s0, v1
	v_mul_f32_e32 v6, 0x4b800000, v1
	s_nop 0
	v_cndmask_b32_e64 v1, v1, v6, s[0:1]
	v_rsq_f32_e32 v1, v1
	s_nop 0
	v_mul_f32_e32 v6, 0x45800000, v1
	v_cndmask_b32_e64 v1, v1, v6, s[0:1]
	global_store_dword v[4:5], v1, off
	s_branch .LBB0_1671

.LBB0_1685:
	s_or_b64 exec, exec, s[6:7]
	v_mul_f32_e32 v6, v21, v21
	v_mul_f32_e32 v7, v23, v23
	v_fmac_f32_e32 v6, v20, v20
	v_fmac_f32_e32 v7, v22, v22
	v_add_f32_e32 v6, v6, v7
	v_mul_f32_e32 v7, v17, v17
	v_fmac_f32_e32 v7, v16, v16
	v_mul_f32_e32 v16, v19, v19
	v_fmac_f32_e32 v16, v18, v18
	v_add_f32_e32 v7, v7, v16
	v_add_f32_e32 v6, v6, v7
	v_mul_f32_e32 v7, v13, v13
	v_fmac_f32_e32 v7, v12, v12
	v_mul_f32_e32 v12, v15, v15
	v_fmac_f32_e32 v12, v14, v14
	v_add_f32_e32 v7, v7, v12
	v_add_f32_e32 v6, v7, v6
	v_mul_f32_e32 v7, v9, v9
	v_fmac_f32_e32 v7, v8, v8
	v_mul_f32_e32 v8, v11, v11
	v_fmac_f32_e32 v8, v10, v10
	v_add_f32_e32 v7, v7, v8
	v_add_f32_e32 v6, v7, v6
	s_nop 1
	v_add_f32_dpp v6, v6, v6 quad_perm:[1,0,3,2] row_mask:0xf bank_mask:0xf
	s_nop 1
	v_add_f32_dpp v6, v6, v6 quad_perm:[2,3,0,1] row_mask:0xf bank_mask:0xf
	s_nop 1
	v_add_f32_dpp v6, v6, v6 row_half_mirror row_mask:0xf bank_mask:0xf
	s_nop 1
	v_add_f32_dpp v6, v6, v6 row_mirror row_mask:0xf bank_mask:0xf
	s_nop 0
	ds_bpermute_b32 v7, v38, v6
	s_waitcnt lgkmcnt(0)
	v_add_f32_e32 v6, v6, v7
	ds_bpermute_b32 v7, v39, v6
	s_and_saveexec_b64 s[6:7], s[2:3]
	s_cbranch_execz .LBB0_1682
	s_waitcnt lgkmcnt(0)
	v_add_f32_e32 v6, v6, v7
	v_fmamk_f32 v6, v6, 0x3a800000, v181
	s_mov_b32 s8, 0x800000
	v_mul_f32_e32 v7, 0x4b800000, v6
	v_cmp_gt_f32_e32 vcc, s8, v6
	v_readlane_b32 s8, v253, 32
	v_readlane_b32 s9, v253, 33
	v_cndmask_b32_e32 v6, v6, v7, vcc
	v_rsq_f32_e32 v8, v6
	v_lshl_add_u64 v[6:7], v[0:1], 2, s[8:9]
	v_mul_f32_e32 v1, 0x45800000, v8
	v_cndmask_b32_e32 v1, v8, v1, vcc
	global_store_dword v[6:7], v1, off
	s_branch .LBB0_1682
